# adds F1 LDS-transposed full-row Y stores and nt hint on GEMM1 epilogue (projection) stores
# speedup vs baseline: 1.0269x; 1.0269x over previous
.LBB0_130:
	s_lshl_b32 s25, s37, 2
	s_lshr_b32 s94, s79, 5
	s_add_i32 s94, s25, s94
	s_mov_b32 s95, 0
	s_lshl_b64 s[94:95], s[94:95], 23
	s_and_b32 s25, s79, 32
	s_lshl_b32 s25, s25, 1
	s_sub_u32 s94, s94, s25
	s_subb_u32 s95, s95, 0
	v_lshl_add_u32 v154, s36, 8, v1
	v_lshlrev_b32_e32 v154, 7, v154
	v_mov_b32_e32 v155, 0
	v_lshl_add_u64 v[156:157], v[138:139], 0, s[94:95]
	v_lshl_add_u64 v[156:157], v[156:157], 0, v[154:155]
	v_and_b32_e32 v158, 1, v1
	v_lshlrev_b32_e32 v159, 6, v158
	v_sub_u32_e32 v160, 0, v159
	v_sub_u32_e32 v161, 0, v158
	v_sub_u32_e32 v162, 0x80, v159
	v_mov_b32_e32 v163, 0
	v_lshl_add_u64 v[164:165], v[156:157], 0, v[160:161]
	v_lshl_add_u64 v[166:167], v[156:157], 0, v[162:163]
	s_mov_b64 s[94:95], 0x1000
	s_mov_b64 s[96:97], 0x3000
	s_mov_b32 vcc_lo, 0x55555555
	s_mov_b32 vcc_hi, 0x55555555
	v_cvt_pk_bf16_f32 v168, v126, v127
	v_cvt_pk_bf16_f32 v169, v128, v129
	v_cvt_pk_bf16_f32 v170, v122, v123
	v_cvt_pk_bf16_f32 v171, v124, v125
	v_cvt_pk_bf16_f32 v172, v78, v79
	v_cvt_pk_bf16_f32 v173, v80, v81
	v_cvt_pk_bf16_f32 v174, v70, v71
	v_cvt_pk_bf16_f32 v175, v72, v73
	s_nop 1
	v_cndmask_b32_dpp v176, v172, v168, vcc quad_perm:[1,0,3,2] row_mask:0xf bank_mask:0xf
	v_cndmask_b32_dpp v177, v173, v169, vcc quad_perm:[1,0,3,2] row_mask:0xf bank_mask:0xf
	v_cndmask_b32_dpp v178, v174, v170, vcc quad_perm:[1,0,3,2] row_mask:0xf bank_mask:0xf
	v_cndmask_b32_dpp v179, v175, v171, vcc quad_perm:[1,0,3,2] row_mask:0xf bank_mask:0xf
	s_not_b64 vcc, vcc
	s_nop 0
	v_cndmask_b32_dpp v172, v168, v172, vcc quad_perm:[1,0,3,2] row_mask:0xf bank_mask:0xf
	v_cndmask_b32_dpp v173, v169, v173, vcc quad_perm:[1,0,3,2] row_mask:0xf bank_mask:0xf
	v_cndmask_b32_dpp v174, v170, v174, vcc quad_perm:[1,0,3,2] row_mask:0xf bank_mask:0xf
	v_cndmask_b32_dpp v175, v171, v175, vcc quad_perm:[1,0,3,2] row_mask:0xf bank_mask:0xf
	s_not_b64 vcc, vcc
	global_store_dwordx4 v[164:165], v[176:179], off nt
	global_store_dwordx4 v[166:167], v[172:175], off nt
	v_cvt_pk_bf16_f32 v180, v118, v119
	v_cvt_pk_bf16_f32 v181, v120, v121
	v_cvt_pk_bf16_f32 v182, v114, v115
	v_cvt_pk_bf16_f32 v183, v116, v117
	v_cvt_pk_bf16_f32 v184, v62, v63
	v_cvt_pk_bf16_f32 v185, v64, v65
	v_cvt_pk_bf16_f32 v186, v54, v55
	v_cvt_pk_bf16_f32 v187, v56, v57
	s_nop 1
	v_cndmask_b32_dpp v188, v184, v180, vcc quad_perm:[1,0,3,2] row_mask:0xf bank_mask:0xf
	v_cndmask_b32_dpp v189, v185, v181, vcc quad_perm:[1,0,3,2] row_mask:0xf bank_mask:0xf
	v_cndmask_b32_dpp v190, v186, v182, vcc quad_perm:[1,0,3,2] row_mask:0xf bank_mask:0xf
	v_cndmask_b32_dpp v191, v187, v183, vcc quad_perm:[1,0,3,2] row_mask:0xf bank_mask:0xf
	s_not_b64 vcc, vcc
	s_nop 0
	v_cndmask_b32_dpp v184, v180, v184, vcc quad_perm:[1,0,3,2] row_mask:0xf bank_mask:0xf
	v_cndmask_b32_dpp v185, v181, v185, vcc quad_perm:[1,0,3,2] row_mask:0xf bank_mask:0xf
	v_cndmask_b32_dpp v186, v182, v186, vcc quad_perm:[1,0,3,2] row_mask:0xf bank_mask:0xf
	v_cndmask_b32_dpp v187, v183, v187, vcc quad_perm:[1,0,3,2] row_mask:0xf bank_mask:0xf
	s_not_b64 vcc, vcc
	global_store_dwordx4 v[164:165], v[188:191], off offset:2048 nt
	global_store_dwordx4 v[166:167], v[184:187], off offset:2048 nt
	v_lshl_add_u64 v[164:165], v[164:165], 0, s[94:95]
	v_lshl_add_u64 v[166:167], v[166:167], 0, s[94:95]
	v_cvt_pk_bf16_f32 v168, v110, v111
	v_cvt_pk_bf16_f32 v169, v112, v113
	v_cvt_pk_bf16_f32 v170, v106, v107
	v_cvt_pk_bf16_f32 v171, v108, v109
	v_cvt_pk_bf16_f32 v172, v46, v47
	v_cvt_pk_bf16_f32 v173, v48, v49
	v_cvt_pk_bf16_f32 v174, v42, v43
	v_cvt_pk_bf16_f32 v175, v44, v45
	s_nop 1
	v_cndmask_b32_dpp v176, v172, v168, vcc quad_perm:[1,0,3,2] row_mask:0xf bank_mask:0xf
	v_cndmask_b32_dpp v177, v173, v169, vcc quad_perm:[1,0,3,2] row_mask:0xf bank_mask:0xf
	v_cndmask_b32_dpp v178, v174, v170, vcc quad_perm:[1,0,3,2] row_mask:0xf bank_mask:0xf
	v_cndmask_b32_dpp v179, v175, v171, vcc quad_perm:[1,0,3,2] row_mask:0xf bank_mask:0xf
	s_not_b64 vcc, vcc
	s_nop 0
	v_cndmask_b32_dpp v172, v168, v172, vcc quad_perm:[1,0,3,2] row_mask:0xf bank_mask:0xf
	v_cndmask_b32_dpp v173, v169, v173, vcc quad_perm:[1,0,3,2] row_mask:0xf bank_mask:0xf
	v_cndmask_b32_dpp v174, v170, v174, vcc quad_perm:[1,0,3,2] row_mask:0xf bank_mask:0xf
	v_cndmask_b32_dpp v175, v171, v175, vcc quad_perm:[1,0,3,2] row_mask:0xf bank_mask:0xf
	s_not_b64 vcc, vcc
	global_store_dwordx4 v[164:165], v[176:179], off nt
	global_store_dwordx4 v[166:167], v[172:175], off nt
	v_cvt_pk_bf16_f32 v180, v102, v103
	v_cvt_pk_bf16_f32 v181, v104, v105
	v_cvt_pk_bf16_f32 v182, v98, v99
	v_cvt_pk_bf16_f32 v183, v100, v101
	v_cvt_pk_bf16_f32 v184, v38, v39
	v_cvt_pk_bf16_f32 v185, v40, v41
	v_cvt_pk_bf16_f32 v186, v34, v35
	v_cvt_pk_bf16_f32 v187, v36, v37
	s_nop 1
	v_cndmask_b32_dpp v188, v184, v180, vcc quad_perm:[1,0,3,2] row_mask:0xf bank_mask:0xf
	v_cndmask_b32_dpp v189, v185, v181, vcc quad_perm:[1,0,3,2] row_mask:0xf bank_mask:0xf
	v_cndmask_b32_dpp v190, v186, v182, vcc quad_perm:[1,0,3,2] row_mask:0xf bank_mask:0xf
	v_cndmask_b32_dpp v191, v187, v183, vcc quad_perm:[1,0,3,2] row_mask:0xf bank_mask:0xf
	s_not_b64 vcc, vcc
	s_nop 0
	v_cndmask_b32_dpp v184, v180, v184, vcc quad_perm:[1,0,3,2] row_mask:0xf bank_mask:0xf
	v_cndmask_b32_dpp v185, v181, v185, vcc quad_perm:[1,0,3,2] row_mask:0xf bank_mask:0xf
	v_cndmask_b32_dpp v186, v182, v186, vcc quad_perm:[1,0,3,2] row_mask:0xf bank_mask:0xf
	v_cndmask_b32_dpp v187, v183, v187, vcc quad_perm:[1,0,3,2] row_mask:0xf bank_mask:0xf
	s_not_b64 vcc, vcc
	global_store_dwordx4 v[164:165], v[188:191], off offset:2048 nt
	global_store_dwordx4 v[166:167], v[184:187], off offset:2048 nt
	v_lshl_add_u64 v[164:165], v[164:165], 0, s[96:97]
	v_lshl_add_u64 v[166:167], v[166:167], 0, s[96:97]
	v_cvt_pk_bf16_f32 v168, v94, v95
	v_cvt_pk_bf16_f32 v169, v96, v97
	v_cvt_pk_bf16_f32 v170, v90, v91
	v_cvt_pk_bf16_f32 v171, v92, v93
	v_cvt_pk_bf16_f32 v172, v30, v31
	v_cvt_pk_bf16_f32 v173, v32, v33
	v_cvt_pk_bf16_f32 v174, v26, v27
	v_cvt_pk_bf16_f32 v175, v28, v29
	s_nop 1
	v_cndmask_b32_dpp v176, v172, v168, vcc quad_perm:[1,0,3,2] row_mask:0xf bank_mask:0xf
	v_cndmask_b32_dpp v177, v173, v169, vcc quad_perm:[1,0,3,2] row_mask:0xf bank_mask:0xf
	v_cndmask_b32_dpp v178, v174, v170, vcc quad_perm:[1,0,3,2] row_mask:0xf bank_mask:0xf
	v_cndmask_b32_dpp v179, v175, v171, vcc quad_perm:[1,0,3,2] row_mask:0xf bank_mask:0xf
	s_not_b64 vcc, vcc
	s_nop 0
	v_cndmask_b32_dpp v172, v168, v172, vcc quad_perm:[1,0,3,2] row_mask:0xf bank_mask:0xf
	v_cndmask_b32_dpp v173, v169, v173, vcc quad_perm:[1,0,3,2] row_mask:0xf bank_mask:0xf
	v_cndmask_b32_dpp v174, v170, v174, vcc quad_perm:[1,0,3,2] row_mask:0xf bank_mask:0xf
	v_cndmask_b32_dpp v175, v171, v175, vcc quad_perm:[1,0,3,2] row_mask:0xf bank_mask:0xf
	s_not_b64 vcc, vcc
	global_store_dwordx4 v[164:165], v[176:179], off nt
	global_store_dwordx4 v[166:167], v[172:175], off nt
	v_cvt_pk_bf16_f32 v180, v86, v87
	v_cvt_pk_bf16_f32 v181, v88, v89
	v_cvt_pk_bf16_f32 v182, v82, v83
	v_cvt_pk_bf16_f32 v183, v84, v85
	v_cvt_pk_bf16_f32 v184, v22, v23
	v_cvt_pk_bf16_f32 v185, v24, v25
	v_cvt_pk_bf16_f32 v186, v18, v19
	v_cvt_pk_bf16_f32 v187, v20, v21
	s_nop 1
	v_cndmask_b32_dpp v188, v184, v180, vcc quad_perm:[1,0,3,2] row_mask:0xf bank_mask:0xf
	v_cndmask_b32_dpp v189, v185, v181, vcc quad_perm:[1,0,3,2] row_mask:0xf bank_mask:0xf
	v_cndmask_b32_dpp v190, v186, v182, vcc quad_perm:[1,0,3,2] row_mask:0xf bank_mask:0xf
	v_cndmask_b32_dpp v191, v187, v183, vcc quad_perm:[1,0,3,2] row_mask:0xf bank_mask:0xf
	s_not_b64 vcc, vcc
	s_nop 0
	v_cndmask_b32_dpp v184, v180, v184, vcc quad_perm:[1,0,3,2] row_mask:0xf bank_mask:0xf
	v_cndmask_b32_dpp v185, v181, v185, vcc quad_perm:[1,0,3,2] row_mask:0xf bank_mask:0xf
	v_cndmask_b32_dpp v186, v182, v186, vcc quad_perm:[1,0,3,2] row_mask:0xf bank_mask:0xf
	v_cndmask_b32_dpp v187, v183, v187, vcc quad_perm:[1,0,3,2] row_mask:0xf bank_mask:0xf
	s_not_b64 vcc, vcc
	global_store_dwordx4 v[164:165], v[188:191], off offset:2048 nt
	global_store_dwordx4 v[166:167], v[184:187], off offset:2048 nt
	v_lshl_add_u64 v[164:165], v[164:165], 0, s[94:95]
	v_lshl_add_u64 v[166:167], v[166:167], 0, s[94:95]
	v_cvt_pk_bf16_f32 v168, v74, v75
	v_cvt_pk_bf16_f32 v169, v76, v77
	v_cvt_pk_bf16_f32 v170, v66, v67
	v_cvt_pk_bf16_f32 v171, v68, v69
	v_cvt_pk_bf16_f32 v172, v14, v15
	v_cvt_pk_bf16_f32 v173, v16, v17
	v_cvt_pk_bf16_f32 v174, v10, v11
	v_cvt_pk_bf16_f32 v175, v12, v13
	s_nop 1
	v_cndmask_b32_dpp v176, v172, v168, vcc quad_perm:[1,0,3,2] row_mask:0xf bank_mask:0xf
	v_cndmask_b32_dpp v177, v173, v169, vcc quad_perm:[1,0,3,2] row_mask:0xf bank_mask:0xf
	v_cndmask_b32_dpp v178, v174, v170, vcc quad_perm:[1,0,3,2] row_mask:0xf bank_mask:0xf
	v_cndmask_b32_dpp v179, v175, v171, vcc quad_perm:[1,0,3,2] row_mask:0xf bank_mask:0xf
	s_not_b64 vcc, vcc
	s_nop 0
	v_cndmask_b32_dpp v172, v168, v172, vcc quad_perm:[1,0,3,2] row_mask:0xf bank_mask:0xf
	v_cndmask_b32_dpp v173, v169, v173, vcc quad_perm:[1,0,3,2] row_mask:0xf bank_mask:0xf
	v_cndmask_b32_dpp v174, v170, v174, vcc quad_perm:[1,0,3,2] row_mask:0xf bank_mask:0xf
	v_cndmask_b32_dpp v175, v171, v175, vcc quad_perm:[1,0,3,2] row_mask:0xf bank_mask:0xf
	s_not_b64 vcc, vcc
	global_store_dwordx4 v[164:165], v[176:179], off nt
	global_store_dwordx4 v[166:167], v[172:175], off nt
	v_cvt_pk_bf16_f32 v180, v58, v59
	v_cvt_pk_bf16_f32 v181, v60, v61
	v_cvt_pk_bf16_f32 v182, v50, v51
	v_cvt_pk_bf16_f32 v183, v52, v53
	v_cvt_pk_bf16_f32 v184, v6, v7
	v_cvt_pk_bf16_f32 v185, v8, v9
	v_cvt_pk_bf16_f32 v186, v2, v3
	v_cvt_pk_bf16_f32 v187, v4, v5
	s_nop 1
	v_cndmask_b32_dpp v188, v184, v180, vcc quad_perm:[1,0,3,2] row_mask:0xf bank_mask:0xf
	v_cndmask_b32_dpp v189, v185, v181, vcc quad_perm:[1,0,3,2] row_mask:0xf bank_mask:0xf
	v_cndmask_b32_dpp v190, v186, v182, vcc quad_perm:[1,0,3,2] row_mask:0xf bank_mask:0xf
	v_cndmask_b32_dpp v191, v187, v183, vcc quad_perm:[1,0,3,2] row_mask:0xf bank_mask:0xf
	s_not_b64 vcc, vcc
	s_nop 0
	v_cndmask_b32_dpp v184, v180, v184, vcc quad_perm:[1,0,3,2] row_mask:0xf bank_mask:0xf
	v_cndmask_b32_dpp v185, v181, v185, vcc quad_perm:[1,0,3,2] row_mask:0xf bank_mask:0xf
	v_cndmask_b32_dpp v186, v182, v186, vcc quad_perm:[1,0,3,2] row_mask:0xf bank_mask:0xf
	v_cndmask_b32_dpp v187, v183, v187, vcc quad_perm:[1,0,3,2] row_mask:0xf bank_mask:0xf
	s_not_b64 vcc, vcc
	global_store_dwordx4 v[164:165], v[188:191], off offset:2048 nt
	global_store_dwordx4 v[166:167], v[184:187], off offset:2048 nt
	s_andn2_b64 vcc, exec, s[0:1]
	s_mov_b64 s[0:1], -1
	s_cbranch_vccnz .LBB0_123
	s_andn2_b64 vcc, exec, s[6:7]
	s_cbranch_vccnz .LBB0_122
	s_barrier
	s_branch .LBB0_122

.LBB0_211:
	s_add_u32 s8, s34, 0xa84000
	s_addc_u32 s9, s35, 0
	s_add_u32 s10, s34, 0xa80000
	s_addc_u32 s11, s35, 0
	s_lshl_b32 s26, s2, 5
	s_lshr_b32 s1, s2, 1
	s_waitcnt vmcnt(0)
	v_lshrrev_b32_e32 v23, 4, v0
	v_bfe_u32 v25, v0, 3, 1
	s_and_b32 s0, s26, 0xfffff000
	s_and_b32 s1, s1, 62
	s_or_b32 s4, s0, s1
	s_lshl_b32 s0, s2, 24
	v_lshl_or_b32 v127, v23, 6, v25
	s_and_b32 s0, s0, 0x3000000
	v_or_b32_e32 v2, s4, v127
	s_add_u32 s5, s20, s0
	v_ashrrev_i32_e32 v3, 31, v2
	s_addc_u32 s18, s21, 0
	v_lshlrev_b64 v[10:11], 7, v[2:3]
	v_or_b32_e32 v2, 0x800, v2
	s_add_u32 s0, s5, 0xc000000
	v_ashrrev_i32_e32 v3, 31, v2
	s_addc_u32 s1, s18, 0
	v_lshlrev_b64 v[14:15], 7, v[2:3]
	v_lshl_add_u64 v[4:5], s[0:1], 0, v[10:11]
	v_lshl_add_u64 v[2:3], s[0:1], 0, v[14:15]
	s_add_u32 s0, s5, 0xc800000
	v_and_b32_e32 v22, 7, v0
	s_addc_u32 s1, s18, 0
	v_mov_b32_e32 v69, 0
	v_lshlrev_b32_e32 v68, 4, v22
	v_lshl_add_u64 v[10:11], s[0:1], 0, v[10:11]
	v_lshl_add_u64 v[12:13], v[4:5], 0, v[68:69]
	v_lshl_add_u64 v[16:17], v[2:3], 0, v[68:69]
	v_lshl_add_u64 v[18:19], v[10:11], 0, v[68:69]
	v_lshl_add_u64 v[10:11], s[0:1], 0, v[14:15]
	global_load_dwordx4 v[2:5], v[12:13], off
	global_load_dwordx4 v[6:9], v[16:17], off
	v_lshl_add_u64 v[20:21], v[10:11], 0, v[68:69]
	global_load_dwordx4 v[10:13], v[18:19], off
	global_load_dwordx4 v[14:17], v[20:21], off
	s_lshl_b32 s4, s33, 6
	s_add_u32 s0, s70, s4
	s_addc_u32 s1, s71, 0
	v_lshlrev_b32_e32 v72, 2, v126
	v_mov_b32_e32 v73, v69
	v_lshlrev_b32_e32 v20, 10, v67
	v_and_b32_e32 v19, 48, v0
	v_lshl_or_b32 v21, v25, 6, v23
	s_movk_i32 s27, 0x110
	v_lshl_add_u64 v[70:71], s[0:1], 0, v[72:73]
	s_add_u32 s0, s68, s4
	v_mul_u32_u24_e32 v23, 0x110, v126
	v_lshlrev_b32_e32 v18, 3, v22
	v_add_u32_e32 v128, 0, v19
	v_lshlrev_b32_e32 v66, 2, v67
	v_or_b32_e32 v22, 0x3000, v20
	v_or_b32_e32 v24, 0x1000, v20
	v_or_b32_e32 v26, 0x1080, v20
	v_or_b32_e32 v28, 0x1100, v20
	v_or_b32_e32 v30, 0x1180, v20
	v_or_b32_e32 v32, 0x1200, v20
	v_or_b32_e32 v34, 0x1280, v20
	v_or_b32_e32 v36, 0x1300, v20
	v_or_b32_e32 v38, 0x1380, v20
	v_or_b32_e32 v40, 0x2000, v20
	v_or_b32_e32 v42, 0x2080, v20
	v_or_b32_e32 v44, 0x2100, v20
	v_or_b32_e32 v46, 0x2180, v20
	v_or_b32_e32 v48, 0x2200, v20
	v_or_b32_e32 v50, 0x2280, v20
	v_or_b32_e32 v52, 0x2300, v20
	v_or_b32_e32 v54, 0x2380, v20
	v_or_b32_e32 v56, 0x3080, v20
	v_or_b32_e32 v58, 0x3100, v20
	v_or_b32_e32 v60, 0x3180, v20
	v_or_b32_e32 v62, 0x3200, v20
	v_or_b32_e32 v64, 0x3280, v20
	v_or_b32_e32 v120, 0x3300, v20
	v_or_b32_e32 v122, 0x3380, v20
	v_mad_u32_u24 v21, v21, s27, 0
	s_addc_u32 s1, s69, 0
	v_add3_u32 v19, v23, v19, 0
	v_lshrrev_b32_e32 v1, 3, v0
	s_mov_b32 s19, 0
	v_lshlrev_b32_e32 v129, 6, v126
	v_lshl_or_b32 v130, s33, 4, v66
	v_lshl_add_u64 v[72:73], s[0:1], 0, v[72:73]
	s_lshl_b32 s28, s3, 5
	v_add_u32_e32 v131, 0x8800, v19
	s_mov_b32 s18, -1
	v_lshlrev_b32_e32 v74, 2, v20
	s_movk_i32 s29, 0x7fff
	s_mov_b32 s30, 0x7060302
	v_lshlrev_b32_e32 v76, 2, v24
	v_lshlrev_b32_e32 v78, 2, v26
	v_lshlrev_b32_e32 v80, 2, v28
	v_lshlrev_b32_e32 v82, 2, v30
	v_lshlrev_b32_e32 v84, 2, v32
	v_lshlrev_b32_e32 v86, 2, v34
	v_lshlrev_b32_e32 v88, 2, v36
	v_lshlrev_b32_e32 v90, 2, v38
	v_lshlrev_b32_e32 v92, 2, v40
	v_lshlrev_b32_e32 v94, 2, v42
	v_lshlrev_b32_e32 v96, 2, v44
	v_lshlrev_b32_e32 v98, 2, v46
	v_lshlrev_b32_e32 v100, 2, v48
	v_lshlrev_b32_e32 v102, 2, v50
	v_lshlrev_b32_e32 v104, 2, v52
	v_lshlrev_b32_e32 v106, 2, v54
	v_lshlrev_b32_e32 v108, 2, v22
	v_lshlrev_b32_e32 v110, 2, v56
	v_lshlrev_b32_e32 v112, 2, v58
	v_lshlrev_b32_e32 v114, 2, v60
	v_lshlrev_b32_e32 v116, 2, v62
	v_lshlrev_b32_e32 v118, 2, v64
	v_lshlrev_b32_e32 v120, 2, v120
	v_lshlrev_b32_e32 v122, 2, v122
	v_add_u32_e32 v132, v21, v68
	v_lshlrev_b32_e32 v124, 1, v18
	s_mov_b32 s1, s2
	v_lshl_add_u32 v178, s33, 3, v67
	v_lshlrev_b32_e32 v179, 3, v126
	v_mul_u32_u24_e32 v177, 0x110, v178
	v_lshl_add_u32 v177, v126, 4, v177
	v_add_u32_e32 v177, 0x11000, v177
	v_mul_u32_u24_e32 v176, 0x110, v126
	v_lshl_add_u32 v176, s33, 5, v176
	v_lshl_add_u32 v176, v67, 3, v176
	v_add_u32_e32 v176, 0xff00, v176
	v_sub_u32_e32 v176, v176, v131

.LBB0_214:
	s_lshl_b32 s4, s1, 5
	s_and_b32 s4, s4, 0xf80
	v_or_b32_e32 v50, s4, v126
	v_lshlrev_b32_e32 v50, 2, v50
	v_or_b32_e32 v51, 64, v50
	v_or_b32_e32 v52, 0x80, v50
	v_or_b32_e32 v53, 0xc0, v50
	v_or_b32_e32 v54, 0x100, v50
	v_or_b32_e32 v55, 0x140, v50
	v_or_b32_e32 v56, 0x180, v50
	v_or_b32_e32 v57, 0x1c0, v50
	global_load_dword v75, v50, s[8:9]
	global_load_dword v77, v50, s[10:11]
	global_load_dword v79, v51, s[8:9]
	global_load_dword v81, v51, s[10:11]
	global_load_dword v83, v52, s[8:9]
	global_load_dword v85, v52, s[10:11]
	global_load_dword v87, v53, s[8:9]
	global_load_dword v89, v53, s[10:11]
	global_load_dword v91, v54, s[8:9]
	global_load_dword v93, v54, s[10:11]
	global_load_dword v95, v55, s[8:9]
	global_load_dword v97, v55, s[10:11]
	global_load_dword v99, v56, s[8:9]
	global_load_dword v101, v56, s[10:11]
	global_load_dword v103, v57, s[8:9]
	global_load_dword v105, v57, s[10:11]
	s_lshr_b32 s4, s1, 1
	s_and_b32 s24, s26, 0xfffff000
	s_add_i32 s31, s1, s3
	s_and_b32 s25, s4, 62
	s_cmpk_gt_i32 s31, 0x7ff
	s_cselect_b64 s[22:23], -1, 0
	s_cmpk_lt_i32 s31, 0x800
	s_cselect_b32 s1, s31, s1
	s_lshl_b32 s4, s1, 5
	s_lshr_b32 s5, s1, 1
	s_lshl_b32 s1, s1, 24
	s_and_b32 s4, s4, 0xfffff000
	s_and_b32 s5, s5, 62
	s_and_b32 s1, s1, 0x3000000
	s_or_b32 s4, s4, s5
	s_waitcnt lgkmcnt(0)
	s_barrier
	s_waitcnt vmcnt(19)
	ds_write_b128 v132, v[2:5]
	s_waitcnt vmcnt(18)
	ds_write_b128 v132, v[6:9] offset:8704
	s_waitcnt vmcnt(17)
	ds_write_b128 v132, v[10:13] offset:128
	s_waitcnt vmcnt(16)
	ds_write_b128 v132, v[14:17] offset:8832
	s_add_u32 s1, s20, s1
	v_or_b32_e32 v2, s4, v127
	s_addc_u32 s36, s21, 0
	v_or_b32_e32 v4, 0x800, v2
	v_ashrrev_i32_e32 v3, 31, v2
	s_add_u32 s4, s1, 0xc000000
	v_ashrrev_i32_e32 v5, 31, v4
	v_lshlrev_b64 v[2:3], 7, v[2:3]
	s_addc_u32 s5, s36, 0
	v_lshlrev_b64 v[4:5], 7, v[4:5]
	v_lshl_add_u64 v[6:7], s[4:5], 0, v[2:3]
	v_lshl_add_u64 v[8:9], s[4:5], 0, v[4:5]
	s_add_u32 s4, s1, 0xc800000
	s_addc_u32 s5, s36, 0
	v_mov_b32_e32 v125, v69
	v_lshl_add_u64 v[2:3], s[4:5], 0, v[2:3]
	v_lshl_add_u64 v[4:5], s[4:5], 0, v[4:5]
	v_lshl_add_u64 v[6:7], v[6:7], 0, v[124:125]
	v_lshl_add_u64 v[8:9], v[8:9], 0, v[124:125]
	v_lshl_add_u64 v[10:11], v[2:3], 0, v[124:125]
	v_lshl_add_u64 v[14:15], v[4:5], 0, v[124:125]
	s_waitcnt lgkmcnt(0)
	s_barrier
	v_lshl_add_u32 v68, s0, 7, v130
	v_lshl_add_u32 v181, s0, 7, v179
	s_or_b32 s0, s25, s24
	v_add_u32_e32 v107, s0, v129
	v_lshl_add_u32 v180, v178, 6, s0
	s_mov_b32 s4, 0
	s_mov_b64 s[0:1], -1
	s_waitcnt vmcnt(14)
	s_waitcnt vmcnt(12)
	s_waitcnt vmcnt(10)
	s_waitcnt vmcnt(8)
	s_waitcnt vmcnt(6)
	s_waitcnt vmcnt(4)
	s_waitcnt vmcnt(2)
	s_waitcnt vmcnt(0)
	global_load_dwordx4 v[2:5], v[6:7], off
	s_nop 0
	global_load_dwordx4 v[6:9], v[8:9], off
	s_nop 0
	global_load_dwordx4 v[10:13], v[10:11], off
	s_nop 0
	global_load_dwordx4 v[14:17], v[14:15], off

.LBB0_216:
	ds_read_b128 v[134:137], v133
	ds_read_b128 v[138:141], v133 offset:64
	ds_read_b128 v[142:145], v133 offset:17408
	ds_read_b128 v[150:153], v133 offset:17472
	ds_read_b128 v[154:157], v133 offset:128
	ds_read_b128 v[158:161], v133 offset:192
	ds_read_b128 v[162:165], v133 offset:17536
	ds_read_b128 v[166:169], v133 offset:17600
	s_waitcnt lgkmcnt(7)
	v_mfma_f32_16x16x32_bf16 v[134:137], v[50:53], v[134:137], 0
	s_cmp_eq_u32 s36, 0
	s_cselect_b64 vcc, -1, 0
	s_cmpk_eq_i32 s36, 0x400
	s_waitcnt lgkmcnt(5)
	v_mfma_f32_16x16x32_bf16 v[142:145], v[50:53], v[142:145], 0
	s_cselect_b64 s[0:1], -1, 0
	s_cmpk_eq_i32 s36, 0x800
	s_cselect_b64 s[4:5], -1, 0
	v_mfma_f32_16x16x32_bf16 v[134:137], v[54:57], v[138:141], v[134:137]
	v_add_u32_e32 v146, s36, v125
	v_ashrrev_i32_e32 v147, 31, v146
	v_lshlrev_b64 v[146:147], 9, v[146:147]
	s_waitcnt lgkmcnt(4)
	v_mfma_f32_16x16x32_bf16 v[138:141], v[54:57], v[150:153], v[142:145]
	s_addk_i32 s36, 0x400
	v_add_u32_e32 v133, 0x1100, v133
	s_cmpk_lg_i32 s36, 0x1000
	s_waitcnt lgkmcnt(1)
	v_mfma_f32_16x16x32_bf16 v[138:141], v[58:61], v[162:165], v[138:141]
	v_cndmask_b32_e64 v145, v123, v121, s[4:5]
	v_cndmask_b32_e64 v144, v115, v113, s[4:5]
	v_cndmask_b32_e64 v145, v145, v119, s[0:1]
	v_mfma_f32_16x16x32_bf16 v[134:137], v[58:61], v[154:157], v[134:137]
	v_cndmask_b32_e64 v144, v144, v111, s[0:1]
	v_cndmask_b32_e32 v150, v145, v117, vcc
	v_lshl_add_u64 v[142:143], v[146:147], 0, v[68:69]
	s_waitcnt lgkmcnt(0)
	v_mfma_f32_16x16x32_bf16 v[138:141], v[62:65], v[166:169], v[138:141]
	v_cndmask_b32_e32 v144, v144, v109, vcc
	v_lshlrev_b64 v[142:143], 1, v[142:143]
	v_lshl_add_u64 v[146:147], s[14:15], 0, v[142:143]
	v_mfma_f32_16x16x32_bf16 v[134:137], v[62:65], v[158:161], v[134:137]
	v_lshl_add_u64 v[142:143], s[12:13], 0, v[142:143]
	s_nop 2
	v_pk_mul_f32 v[152:153], v[150:151], v[138:139] op_sel_hi:[0,1]
	v_pk_mul_f32 v[156:157], v[150:151], v[140:141] op_sel_hi:[0,1]
	s_nop 1
	v_pk_mul_f32 v[154:155], v[150:151], v[134:135] op_sel_hi:[0,1]
	v_pk_mul_f32 v[150:151], v[150:151], v[136:137] op_sel_hi:[0,1]
	v_pk_fma_f32 v[134:135], v[144:145], v[134:135], v[152:153] op_sel_hi:[0,1,1]
	v_pk_fma_f32 v[136:137], v[144:145], v[136:137], v[156:157] op_sel_hi:[0,1,1]
	v_pk_fma_f32 v[138:139], v[144:145], v[138:139], v[154:155] op_sel_hi:[0,1,1] neg_lo:[0,0,1] neg_hi:[0,0,1]
	v_pk_fma_f32 v[140:141], v[144:145], v[140:141], v[150:151] op_sel_hi:[0,1,1] neg_lo:[0,0,1] neg_hi:[0,0,1]
	v_cvt_pk_bf16_f32 v134, v134, v135
	v_cvt_pk_bf16_f32 v135, v136, v137
	v_cvt_pk_bf16_f32 v136, v138, v139
	v_cvt_pk_bf16_f32 v137, v140, v141
	v_add_u32_e32 v200, v176, v133
	ds_write_b64 v200, v[134:135]
	ds_write_b64 v200, v[136:137] offset:17408
	s_cbranch_scc1 .LBB0_216
	s_waitcnt lgkmcnt(0)
	s_barrier
	ds_read_b128 v[184:187], v177
	ds_read_b128 v[188:191], v177 offset:1088
	ds_read_b128 v[192:195], v177 offset:17408
	ds_read_b128 v[196:199], v177 offset:18496
	s_and_b32 s6, s24, 1
	v_add_u32_e32 v182, s6, v180
	v_lshlrev_b32_e32 v182, 10, v182
	v_lshl_add_u32 v182, v181, 1, v182
	v_add_u32_e32 v183, 0x40000, v182
	s_waitcnt lgkmcnt(0)
	s_barrier
	global_store_dwordx4 v182, v[184:187], s[14:15]
	global_store_dwordx4 v183, v[188:191], s[14:15]
	global_store_dwordx4 v182, v[192:195], s[12:13]
	global_store_dwordx4 v183, v[196:199], s[12:13]
	s_mov_b32 s4, 1
	s_mov_b64 s[0:1], 0
	s_and_b64 vcc, exec, s[24:25]
	s_cbranch_vccz .LBB0_215
	s_add_i32 s26, s26, s28
	s_and_b64 vcc, exec, s[22:23]
	s_mov_b32 s1, s31
	s_cbranch_vccz .LBB0_212
	s_waitcnt vmcnt(5)
	v_mov_b32_e32 v2, v67
